# GEMM tile order: group-M (WGM) 2->4 for the in-projection (P1) and FF1 (P7) GEMMs (4 pm x 8 pn per XCD round instead of 2 x 16: less L2-miss traffic); on top of v15
# speedup vs baseline: 1.0202x; 1.0202x over previous
; #define LAS __attribute__((address_space(3)))
; __device__ __forceinline__ unsigned xb_ld(unsigned* p)              { return __hip_atomic_load(p, __ATOMIC_RELAXED, __HIP_MEMORY_SCOPE_AGENT); }
; __device__ __forceinline__ void xcd_barrier_complete(unsigned* bar, unsigned x, unsigned& nloc, unsigned& nx) {
;     const unsigned G = gridDim.x * gridDim.y * gridDim.z;
;     unsigned sum, cnt, mine, sp = 0u;
;     for (;;) {
;         sum = 0u; cnt = 0u; mine = 0u;
; #pragma unroll
;         for (unsigned j = 0; j < 16; ++j) { const unsigned c = xb_ld(&bar[XB_XCNT(j)]); sum += c; cnt += (c > 0u) ? 1u : 0u; mine = (j == x) ? c : mine; }
; __global__ void __launch_bounds__(NTHR, 2) fwd_megakernel(Args args) {
;     ...
;     unsigned char* ws = args.ws;
;     float* rn2 = (float*)(ws + WS_RN2);
;     float* logf = (float*)(ws + WS_LOGF); float* cs = (float*)(ws + WS_CS);
;     bf16* Win_t = (bf16*)(ws + WS_WIN); bf16* Wc_t = (bf16*)(ws + WS_WC); bf16* Wa_t = (bf16*)(ws + WS_WA); bf16* Wmix_t = (bf16*)(ws + WS_WMIX);
;     bf16* W1_t = (bf16*)(ws + WS_W1); bf16* W2_t = (bf16*)(ws + WS_W2);
;     bf16* Z = (bf16*)(ws + WS_Z); bf16* XN = (bf16*)(ws + WS_XN); bf16* CONVY = (bf16*)(ws + WS_CONVY); bf16* ATTO = (bf16*)(ws + WS_ATTO);
;     bf16* XG = (bf16*)(ws + WS_Z + 256 * MiB);
;     float* rowss = (float*)(ws + WS_RSS);
;     float* xres = args.out;
;     volatile LAS unsigned* bst = (volatile LAS unsigned*)(L + att::LDS_BYTES + 65536 + 64);
;     if (tid0 < 2) bst[tid0] = 0u;
;     __syncthreads();
;     const XcdBarrier xbar = xcd_barrier_post((unsigned*)(ws + WS_BAR), bst);
.LBB0_5:
	s_or_b64 exec, exec, s[0:1]
	s_lshr_b32 s97, s6, 6
	s_lshl_b32 s0, s2, 3
	s_add_i32 s24, s97, s0
	s_lshl_b32 s80, s70, 3
	s_add_u32 s88, s68, 0x24000000
	s_addc_u32 s89, s69, 0
	s_add_u32 s18, s68, 0x100000
	s_addc_u32 s19, s69, 0
	s_add_u32 s20, s68, 0x180000
	s_addc_u32 s21, s69, 0
	s_add_u32 s26, s68, 0x200000
	s_addc_u32 s27, s69, 0
	s_add_u32 s28, s68, 0x2a00000
	s_addc_u32 s29, s69, 0
	s_add_u32 s30, s68, 0x2e00000
	s_addc_u32 s31, s69, 0
	s_add_u32 s34, s68, 0x3200000
	s_addc_u32 s35, s69, 0
	s_add_u32 s36, s68, 0x3a00000
	s_addc_u32 s37, s69, 0
	s_add_u32 s38, s68, 0x5a00000
	s_addc_u32 s39, s69, 0
	s_add_u32 s4, s68, 0x8000000
	s_addc_u32 s5, s69, 0
	s_add_u32 s6, s68, 0x1c000000
	s_addc_u32 s7, s69, 0
	s_add_u32 s8, s68, 0x20000000
	s_addc_u32 s9, s69, 0
	s_add_u32 s42, s68, 0x22000000
	s_addc_u32 s43, s69, 0
	s_add_u32 s10, s68, 0x18000000
	s_addc_u32 s11, s69, 0
	s_add_u32 s12, s68, 0x20000
	s_addc_u32 s13, s69, 0
	s_cmpk_lt_i32 s2, 0x100
	s_cselect_b64 s[0:1], -1, 0
	v_writelane_b32 v252, s0, 26
	v_lshrrev_b32_e32 v1, 20, v0
	v_lshrrev_b32_e32 v0, 10, v0
	v_writelane_b32 v252, s1, 27
	s_lshl_b32 s0, s97, 14
	s_add_i32 s0, s0, 0
	s_cmpk_lt_i32 s24, 0x7800
	v_writelane_b32 v252, s0, 28
	s_cselect_b64 s[0:1], -1, 0
	v_writelane_b32 v252, s0, 29
	s_ashr_i32 s25, s24, 31
	v_or_b32_e32 v0, v0, v1
	v_writelane_b32 v252, s1, 30
	s_lshl_b64 s[0:1], s[24:25], 13
	v_writelane_b32 v252, s0, 31
	s_cmpk_lt_i32 s24, 0x4000
	s_mul_i32 s71, s71, s70
	v_writelane_b32 v252, s1, 32
	s_cselect_b64 s[0:1], -1, 0
	v_writelane_b32 v252, s0, 33
	s_mul_i32 s71, s71, s16
	v_mbcnt_lo_u32_b32 v1, -1, 0
	v_writelane_b32 v252, s1, 34
	s_add_u32 s0, s68, 0x4200
	s_addc_u32 s1, s69, 0
	v_writelane_b32 v252, s0, 35
	v_mov_b32_e32 v193, 0
	v_mov_b32_e32 v237, 0x358637bd
	v_writelane_b32 v252, s1, 36
	s_add_u32 s0, s68, 0x4400
	s_addc_u32 s1, s69, 0
	v_writelane_b32 v252, s0, 37
	v_mov_b32_e32 v206, 0x260
	v_mbcnt_hi_u32_b32 v203, -1, v1
	v_writelane_b32 v252, s1, 38
	s_add_u32 s0, s68, 0x4500
	s_addc_u32 s1, s69, 0
	v_writelane_b32 v252, s0, 39
	v_mov_b32_e32 v207, 0xff800000
	v_mov_b32_e32 v208, 0x5000
	v_writelane_b32 v252, s1, 40
	s_add_u32 s0, s68, 0x4600
	s_addc_u32 s1, s69, 0
	v_writelane_b32 v252, s0, 41
	v_mov_b64_e32 v[232:233], 0x200
	v_mov_b64_e32 v[204:205], 0x1ff
	v_writelane_b32 v252, s1, 42
	s_add_u32 s0, s68, 0x4700
	s_addc_u32 s1, s69, 0
	v_writelane_b32 v252, s0, 43
	v_mov_b64_e32 v[250:251], 0x7ff
	s_movk_i32 s61, 0x4000
	v_writelane_b32 v252, s1, 44
	s_add_u32 s0, s68, 0x4800
	s_addc_u32 s1, s69, 0
	v_writelane_b32 v252, s0, 45
	s_movk_i32 s81, 0x7fff
	s_mov_b32 s96, 0xffff0000
	v_writelane_b32 v252, s1, 46
	s_add_u32 s0, s68, 0x4900
	s_addc_u32 s1, s69, 0
	v_writelane_b32 v252, s0, 47
	s_movk_i32 s84, 0x1000
	s_movk_i32 s85, 0x5000
	v_writelane_b32 v252, s1, 48
	s_add_u32 s0, s68, 0x4a00
	s_addc_u32 s1, s69, 0
	v_writelane_b32 v252, s0, 49
	s_mov_b32 s90, 0x42000000
	s_mov_b32 s60, 0x3e0293ee
	v_writelane_b32 v252, s1, 50
	s_add_u32 s0, s68, 0x4b00
	s_addc_u32 s1, s69, 0
	v_writelane_b32 v252, s0, 51
	s_nop 1
	v_writelane_b32 v252, s1, 52
	s_add_u32 s0, s68, 0x4c00
	s_addc_u32 s1, s69, 0
	v_writelane_b32 v252, s0, 53
	s_nop 1
	v_writelane_b32 v252, s1, 54
	s_add_u32 s0, s68, 0x4d00
	s_addc_u32 s1, s69, 0
	s_add_u32 s82, s68, 0x4e00
	v_writelane_b32 v252, s0, 55
	s_addc_u32 s83, s69, 0
	s_nop 0
	v_writelane_b32 v252, s1, 56
	s_add_u32 s0, s68, 0x4f00
	s_addc_u32 s1, s69, 0
	s_add_u32 s72, s68, 0x5000
	s_addc_u32 s73, s69, 0
	s_add_u32 s74, s68, 0x5100
	s_addc_u32 s75, s69, 0
	s_add_u32 s76, s68, 0x5200
	s_addc_u32 s77, s69, 0
	s_add_u32 s78, s68, 0x5300
	s_addc_u32 s79, s69, 0
	s_cmp_eq_u32 s3, 15
	s_cselect_b64 s[22:23], -1, 0
	v_writelane_b32 v252, s22, 57
	s_cmp_eq_u32 s3, 14
	s_nop 0
	v_writelane_b32 v252, s23, 58
	s_cselect_b64 s[22:23], -1, 0
	v_writelane_b32 v252, s22, 59
	s_cmp_eq_u32 s3, 13
	s_nop 0
	v_writelane_b32 v252, s23, 60
	s_cselect_b64 s[22:23], -1, 0
	v_writelane_b32 v252, s22, 61
	s_cmp_eq_u32 s3, 12
	s_nop 0
	v_writelane_b32 v252, s23, 62
	s_cselect_b64 s[22:23], -1, 0
	v_writelane_b32 v252, s22, 63
	s_cmp_eq_u32 s3, 11
	s_nop 0
	v_writelane_b32 v253, s23, 0
	s_cselect_b64 s[22:23], -1, 0
	v_writelane_b32 v253, s22, 1
	s_cmp_eq_u32 s3, 10
	s_nop 0
	v_writelane_b32 v253, s23, 2
	s_cselect_b64 s[22:23], -1, 0
	v_writelane_b32 v253, s22, 3
	s_cmp_eq_u32 s3, 9
	s_nop 0
	v_writelane_b32 v253, s23, 4
	s_cselect_b64 s[22:23], -1, 0
	v_writelane_b32 v253, s22, 5
	s_cmp_eq_u32 s3, 8
	s_nop 0
	v_writelane_b32 v253, s23, 6
	s_cselect_b64 s[22:23], -1, 0
	v_writelane_b32 v253, s22, 7
	s_cmp_eq_u32 s3, 7
	s_nop 0
	v_writelane_b32 v253, s23, 8
	s_cselect_b64 s[22:23], -1, 0
	v_writelane_b32 v253, s22, 9
	s_cmp_eq_u32 s3, 6
	s_nop 0
	v_writelane_b32 v253, s23, 10
	s_cselect_b64 s[22:23], -1, 0
	v_writelane_b32 v253, s22, 11
	s_cmp_eq_u32 s3, 5
	s_nop 0
	v_writelane_b32 v253, s23, 12
	s_cselect_b64 s[22:23], -1, 0
	v_writelane_b32 v253, s22, 13
	s_cmp_eq_u32 s3, 4
	s_nop 0
	v_writelane_b32 v253, s23, 14
	s_cselect_b64 s[22:23], -1, 0
	v_writelane_b32 v253, s22, 15
	s_cmp_eq_u32 s3, 3
	s_nop 0
	v_writelane_b32 v253, s23, 16
	s_cselect_b64 s[22:23], -1, 0
	v_writelane_b32 v253, s22, 17
	s_cmp_eq_u32 s3, 2
	s_nop 0
	v_writelane_b32 v253, s23, 18
	s_cselect_b64 s[22:23], -1, 0
	v_writelane_b32 v253, s22, 19
	s_cmp_eq_u32 s3, 1
	s_nop 0
	v_writelane_b32 v253, s23, 20
	s_cselect_b64 s[22:23], -1, 0
	v_writelane_b32 v253, s22, 21
	s_cmp_eq_u32 s3, 0
	s_nop 0
	v_writelane_b32 v253, s23, 22
	s_cselect_b64 s[22:23], -1, 0
	s_lshl_b32 s3, s17, 2
	s_add_u32 s3, s14, s3
	v_writelane_b32 v253, s22, 23
	s_addc_u32 s14, s15, 0
	s_nop 0
;     __host__ __device__ bool next(int i, Unit& u) const {
;         const long L = (long)i * G + c; if (L >= nwg) return false;
;         int wgid = (int)L; { const int q = nwg / NXCD, r = nwg % NXCD, xcd = wgid % NXCD, off = wgid / NXCD; wgid = (xcd < r ? xcd * (q + 1) : r * (q + 1) + (xcd - r) * q) + off; }
;         const int nig = WGM * nN, gid = wgid / nig, fm = gid * WGM, gsz = (nM - fm) < WGM ? (nM - fm) : WGM;
;         u.pm = fm + ((wgid % nig) % gsz); u.pn = (wgid % nig) / gsz; return true;
	v_writelane_b32 v253, s23, 24
	s_add_u32 s22, s3, 0x1400
	s_addc_u32 s23, s14, 0
	v_writelane_b32 v253, s22, 25
	s_nop 1
	v_writelane_b32 v253, s23, 26
	s_add_u32 s22, s3, 0x2400
	s_addc_u32 s23, s14, 0
	v_writelane_b32 v253, s22, 27
	s_add_u32 s14, s68, 0x7400
	s_addc_u32 s15, s69, 0
	v_writelane_b32 v253, s23, 28
	v_writelane_b32 v253, s14, 29
	s_nop 1
	v_writelane_b32 v253, s15, 30
	s_add_u32 s14, s68, 0x7500
	s_addc_u32 s15, s69, 0
	v_writelane_b32 v253, s14, 31
	s_cmp_lt_i32 s2, 8
	s_nop 0
	v_writelane_b32 v253, s15, 32
	s_cselect_b64 s[14:15], -1, 0
	v_writelane_b32 v253, s14, 33
	s_ashr_i32 s3, s2, 31
	s_nop 0
	v_writelane_b32 v253, s15, 34
	s_lshl_b64 s[14:15], s[2:3], 2
	s_add_u32 s14, s18, s14
	v_writelane_b32 v253, s18, 35
	s_addc_u32 s15, s19, s15
	s_nop 0
	v_writelane_b32 v253, s19, 36
	v_writelane_b32 v253, s14, 37
	s_nop 1
	v_writelane_b32 v253, s15, 38
	s_lshl_b64 s[14:15], s[2:3], 16
	v_writelane_b32 v253, s20, 39
	s_add_u32 s14, s20, s14
	v_writelane_b32 v253, s21, 40
	s_addc_u32 s15, s21, s15
	v_writelane_b32 v253, s14, 41
	s_cmpk_lt_i32 s2, 0xa00
	s_nop 0
	v_writelane_b32 v253, s15, 42
	s_cselect_b64 s[14:15], -1, 0
	v_writelane_b32 v253, s14, 43
	s_ashr_i32 s33, s70, 31
	s_nop 0
	v_writelane_b32 v253, s15, 44
	s_lshr_b32 s14, s3, 29
	s_add_i32 s14, s2, s14
	s_ashr_i32 s15, s14, 3
	s_and_b32 s14, s14, -8
	s_sub_i32 s14, s2, s14
	s_add_u32 s17, s68, 0x8001800
	v_writelane_b32 v253, s17, 45
	s_addc_u32 s17, s69, 0
	v_writelane_b32 v253, s17, 46
	s_add_u32 s17, s68, 0x8002000
	v_writelane_b32 v253, s17, 47
	s_addc_u32 s17, s69, 0
	v_writelane_b32 v253, s17, 48
	s_add_u32 s17, s68, 0x8000
	v_writelane_b32 v253, s17, 49
	s_addc_u32 s17, s69, 0
	v_writelane_b32 v253, s17, 50
	s_ashr_i32 s17, s70, 3
	s_mul_i32 s17, s17, s14
	s_add_i32 s17, s17, s15
	s_and_b32 s18, s70, 7
	s_add_u32 s20, s68, 0x8003000
	s_addc_u32 s21, s69, 0
	v_writelane_b32 v253, s20, 51
	s_cmpk_lt_i32 s2, 0x200
	s_nop 0
	v_writelane_b32 v253, s21, 52
	s_cselect_b64 s[20:21], -1, 0
	v_writelane_b32 v253, s20, 53
	s_lshl_b32 s19, s14, 6
	s_nop 0
	v_writelane_b32 v253, s21, 54
	s_add_u32 s20, s68, 0x8004000
	s_addc_u32 s21, s69, 0
	v_writelane_b32 v253, s20, 55
	s_cmpk_lt_i32 s2, 0x800
	s_nop 0
	v_writelane_b32 v253, s21, 56
	s_cselect_b64 s[20:21], -1, 0
	v_writelane_b32 v253, s20, 57
	s_nop 1
	v_writelane_b32 v253, s21, 58
	s_lshl_b32 s20, s14, 8
	s_cmp_lt_i32 s14, 0
	s_mul_i32 s21, s14, 0x41
	s_cselect_b32 s19, s21, s19
	s_movk_i32 s21, 0x141
	s_cselect_b32 s21, s21, 0x140
	s_mul_i32 s21, s14, s21
	s_mulk_i32 s14, 0x101
	s_cselect_b32 s22, s14, s20
	s_add_i32 s21, s21, s15
	s_mul_hi_i32 s14, s21, 0x66666667
	s_lshr_b32 s20, s14, 31
	s_ashr_i32 s14, s14, 6
	s_add_i32 s14, s14, s20
	s_mul_i32 s20, s14, 0xa0
	s_sub_i32 s20, s21, s20
	s_lshr_b32 s21, s20, 2
	s_lshl_b32 s21, s21, 1
	s_mov_b32 s23, s21
	s_and_b32 s20, s20, 3
	s_lshl_b32 s14, s14, 2
	s_add_i32 s44, s14, s20
	s_ashr_i32 s14, s21, 1
	v_writelane_b32 v253, s14, 59
	s_lshr_b32 s14, s21, 1
	s_add_u32 s20, s68, 0x18fffc
	s_addc_u32 s21, s69, 0
	v_writelane_b32 v253, s20, 60
	s_nop 1
	v_writelane_b32 v253, s21, 61
	s_add_u32 s20, s68, 0x19fffc
	s_addc_u32 s21, s69, 0
	v_writelane_b32 v253, s20, 62
	s_nop 1
	v_writelane_b32 v253, s21, 63
	s_add_u32 s20, s68, 0x1afffc
	s_addc_u32 s21, s69, 0
	v_writelane_b32 v254, s20, 0
	s_nop 1
	v_writelane_b32 v254, s21, 1
	s_add_u32 s20, s68, 0x1bfffc
	s_addc_u32 s21, s69, 0
	v_writelane_b32 v254, s20, 2
	s_nop 1
	v_writelane_b32 v254, s21, 3
	s_add_u32 s20, s68, 0x1cfffc
	s_addc_u32 s21, s69, 0
	v_writelane_b32 v254, s20, 4
	s_nop 1
	v_writelane_b32 v254, s21, 5
	s_add_u32 s20, s68, 0x1dfffc
	s_addc_u32 s21, s69, 0
	v_writelane_b32 v254, s20, 6
	s_nop 1
	v_writelane_b32 v254, s21, 7
	s_add_u32 s20, s68, 0x1efffc
	s_addc_u32 s21, s69, 0
	v_writelane_b32 v254, s20, 8
	s_nop 1
	v_writelane_b32 v254, s21, 9
	s_add_u32 s20, s68, 0x1ffffc
	s_addc_u32 s21, s69, 0
	v_writelane_b32 v254, s20, 10
	s_cmp_eq_u32 s18, 0
	s_cselect_b32 s17, s17, s2
	v_writelane_b32 v254, s21, 11
	v_writelane_b32 v254, s17, 12
	s_add_i32 s17, s19, s15
	s_ashr_i32 s18, s17, 31
	s_lshr_b32 s18, s18, 28
	s_add_i32 s18, s17, s18
	s_and_b32 s19, s18, 0xfff0
	s_sub_i32 s17, s17, s19
	s_bfe_u32 s19, s17, 0x10007
	s_add_i32 s19, s17, s19
	s_and_b32 s20, s19, 0xfe
	s_sub_i32 s17, s17, s20
	s_ashr_i32 s18, s18, 4
	s_bfe_i32 s19, s19, 0x80000
	s_lshl_b32 s18, s18, 1
	s_sext_i32_i16 s19, s19
	s_sext_i32_i8 s17, s17
	s_add_i32 s46, s18, s17
	s_lshr_b32 s18, s19, 1
	s_ashr_i32 s47, s46, 31
	s_bfe_i64 s[40:41], s[18:19], 0x100000
	s_ashr_i32 s17, s19, 1
	s_lshl_b64 s[18:19], s[46:47], 19
	s_lshl_b64 s[20:21], s[40:41], 19
	v_writelane_b32 v254, s17, 13
	s_add_u32 s48, s28, s20
	v_writelane_b32 v254, s28, 14
	s_addc_u32 s49, s29, s21
	s_mov_b64 s[68:69], 0x80
	v_writelane_b32 v254, s29, 15
	s_add_u32 s28, s48, 0x40000
	s_addc_u32 s29, s49, 0
	v_writelane_b32 v254, s28, 16
	s_nop 1
	v_writelane_b32 v254, s29, 17
	s_add_u32 s28, s8, s18
	s_addc_u32 s29, s9, s19
	s_add_u32 s50, s28, 0x40000
	v_writelane_b32 v254, s28, 18
	s_addc_u32 s51, s29, 0
	s_nop 0
	v_writelane_b32 v254, s29, 19
	v_writelane_b32 v254, s50, 20
	s_add_u32 s28, s48, 0x40080
	s_nop 0
	v_writelane_b32 v254, s51, 21
	v_writelane_b32 v254, s48, 22
	s_addc_u32 s29, s49, 0
	s_add_u32 s20, s30, s20
	v_writelane_b32 v254, s49, 23
	v_writelane_b32 v254, s28, 24
	s_nop 1
	v_writelane_b32 v254, s29, 25
	v_writelane_b32 v254, s30, 26
	s_addc_u32 s21, s31, s21
	s_add_u32 s28, s20, 0x40000
	v_writelane_b32 v254, s31, 27
	s_addc_u32 s29, s21, 0
	v_writelane_b32 v254, s28, 28
	s_add_u32 s18, s42, s18
	s_addc_u32 s19, s43, s19
	v_writelane_b32 v254, s29, 29
; #define PG8_WAIT_V(n) asm volatile("s_waitcnt vmcnt(" #n ")" ::: "memory")
; #define PG8_BAR __builtin_amdgcn_s_barrier()
;     __host__ __device__ bool next(int i, Unit& u) const {
;     ...
;         int wgid = (int)L; { const int q = nwg / NXCD, r = nwg % NXCD, xcd = wgid % NXCD, off = wgid / NXCD; wgid = (xcd < r ? xcd * (q + 1) : r * (q + 1) + (xcd - r) * q) + off; }
;         const int nig = WGM * nN, gid = wgid / nig, fm = gid * WGM, gsz = (nM - fm) < WGM ? (nM - fm) : WGM;
;         u.pm = fm + ((wgid % nig) % gsz); u.pn = (wgid % nig) / gsz; return true;
; template <class Epi, class Sched, bool ALIGN_EPI = false, bool SP2 = false>
; __device__ __forceinline__ void gemm_phase(PG8_LAS unsigned char* lds, const Gemm g, const Sched& S, const Epi& E) {
;     ...
;     const char* cA = (const char*)g.A + (size_t)cur.pm * tstepA; const char* cB = (const char*)g.Bt + (size_t)cur.pn * tstepB;
;     S.a_ready(cur);
;     if constexpr (SP2) {
;         PG8_STAGE(PG8_SB(0, 0), cB, voffB); PG8_STAGE(PG8_SB(0, 1), cB + hstepB, voffB); PG8_STAGE(PG8_SA(0, 0), cA, voffA); PG8_STAGE(PG8_SA(0, 1), cA + hstepA, voffA);
;         if (wr == 1) PG8_BAR;
;         PG8_WAIT_V(2); PG8_BAR;
;         PG8_STAGE(PG8_SB(1, 0), cB + kstep, voffB); PG8_STAGE(PG8_SA(1, 0), cA + kstep, voffA); PG8_STAGE(PG8_SB(1, 1), cB + hstepB + kstep, voffB);
;         PG8_WAIT_V(6); PG8_BAR;
;     } else {
;         PG8_STAGE(PG8_SB(0, 0), cB, voffB); PG8_STAGE(PG8_SA(0, 0), cA, voffA); PG8_STAGE(PG8_SB(0, 1), cB + hstepB, voffB); PG8_STAGE(PG8_SA(0, 1), cA + hstepA, voffA);
;         if (wr == 1) PG8_BAR;
;         PG8_WAIT_V(4); PG8_BAR;
;         PG8_STAGE(PG8_SB(1, 0), cB + kstep, voffB); PG8_STAGE(PG8_SA(1, 0), cA + kstep, voffA); PG8_STAGE(PG8_SB(1, 1), cB + hstepB + kstep, voffB);
;         PG8_WAIT_V(6); PG8_BAR;
;     }
;     for (;;) {
;         const bool has_next = S.next(ui + 1, nxt);
;         const char* nA = has_next ? (const char*)g.A + (size_t)nxt.pm * tstepA : cA; const char* nB = has_next ? (const char*)g.Bt + (size_t)nxt.pn * tstepB : cB;
;         for (int t = 0; t < nt; t += 2) {
;             const bool last = (t == nt - 2);
;             const char* a1 = cA + (size_t)(t + 1) * kstep;
;             const char* a2 = last ? nA : cA + (size_t)(t + 2) * kstep; const char* b2 = last ? nB : cB + (size_t)(t + 2) * kstep;
;             const char* a3 = a2 + kstep; const char* b3 = b2 + kstep;
	v_writelane_b32 v254, s42, 30
	v_writelane_b32 v254, s43, 31
	s_add_u32 s28, s18, 0x40000
	v_writelane_b32 v254, s18, 32
	s_addc_u32 s29, s19, 0
	s_nop 0
	v_writelane_b32 v254, s19, 33
	v_writelane_b32 v254, s28, 34
	s_add_u32 s18, s20, 0x40080
	s_nop 0
	v_writelane_b32 v254, s29, 35
	v_writelane_b32 v254, s20, 36
	s_addc_u32 s19, s21, 0
	s_add_i32 s15, s22, s15
	s_ashr_i32 s17, s15, 31
	v_writelane_b32 v254, s21, 37
	s_lshr_b32 s17, s17, 25
	v_writelane_b32 v254, s18, 38
	s_add_i32 s17, s15, s17
	s_mov_b32 s28, s87
	v_writelane_b32 v254, s19, 39
	s_and_b32 s18, s17, 0xff80
	s_sub_i32 s15, s15, s18
	s_lshr_b32 s18, s15, 2
	s_lshl_b32 s18, s18, 1
	s_mov_b32 s19, s18
	s_and_b32 s15, s15, 3
	s_ashr_i32 s17, s17, 7
	s_nop 0
	s_lshl_b32 s17, s17, 2
	s_nop 0
	s_nop 0
	s_add_i32 s22, s17, s15
	s_ashr_i32 s15, s18, 1
	v_writelane_b32 v254, s15, 40
	s_lshr_b32 s18, s18, 1
	s_mov_b32 s20, s22
	s_ashr_i32 s23, s22, 31
	s_bfe_i64 s[18:19], s[18:19], 0x100000
	v_writelane_b32 v254, s20, 41
	s_lshl_b64 s[18:19], s[18:19], 20
	s_nop 0
	v_writelane_b32 v254, s21, 42
	s_lshl_b64 s[20:21], s[22:23], 20
	s_add_u32 s18, s36, s18
	s_addc_u32 s19, s37, s19
	s_add_u32 s22, s18, 0x80000
	s_addc_u32 s23, s19, 0
	v_writelane_b32 v254, s22, 43
	s_add_u32 s20, s10, s20
	s_addc_u32 s21, s11, s21
	v_writelane_b32 v254, s23, 44
	s_add_u32 s22, s20, 0x80000
	v_writelane_b32 v254, s20, 45
	s_addc_u32 s23, s21, 0
	s_nop 0
	v_writelane_b32 v254, s21, 46
	v_writelane_b32 v254, s22, 47
	s_add_u32 s20, s18, 0x80080
	s_nop 0
	v_writelane_b32 v254, s23, 48
	v_writelane_b32 v254, s18, 49
	s_addc_u32 s21, s19, 0
	s_nop 0
	v_writelane_b32 v254, s19, 50
	v_writelane_b32 v254, s20, 51
	s_lshl_b64 s[18:19], s[46:47], 22
	s_nop 0
	v_writelane_b32 v254, s21, 52
	s_lshl_b64 s[20:21], s[40:41], 22
	s_add_u32 s20, s38, s20
	v_writelane_b32 v254, s38, 53
	s_addc_u32 s21, s39, s21
	s_add_u32 s22, s20, 0x200000
	v_writelane_b32 v254, s39, 54
	s_addc_u32 s23, s21, 0
	v_writelane_b32 v254, s22, 55
	s_add_u32 s18, s4, s18
	s_addc_u32 s19, s5, s19
	v_writelane_b32 v254, s23, 56
	s_add_u32 s22, s18, 0x200000
	v_writelane_b32 v254, s18, 57
	s_addc_u32 s23, s19, 0
	s_movk_i32 s39, 0xbfff
	v_writelane_b32 v254, s19, 58
	v_writelane_b32 v254, s22, 59
	s_add_u32 s18, s20, 0x200080
	s_nop 0
	v_writelane_b32 v254, s23, 60
	v_writelane_b32 v254, s20, 61
	s_addc_u32 s19, s21, 0
	s_ashr_i32 s45, s44, 31
	v_writelane_b32 v254, s21, 62
	v_writelane_b32 v254, s18, 63
	s_bfe_i64 s[14:15], s[14:15], 0x100000
	s_lshl_b64 s[14:15], s[14:15], 20
	v_writelane_b32 v255, s19, 0
	s_mov_b32 s18, s44
	v_writelane_b32 v255, s18, 1
	s_nop 1
	v_writelane_b32 v255, s19, 2
	s_lshl_b64 s[18:19], s[44:45], 20
	s_add_u32 s14, s26, s14
	v_writelane_b32 v255, s26, 3
	s_addc_u32 s15, s27, s15
	s_add_u32 s20, s14, 0x80000
	v_writelane_b32 v255, s27, 4
	s_addc_u32 s21, s15, 0
	v_writelane_b32 v255, s20, 5
	s_add_u32 s18, s6, s18
	s_addc_u32 s19, s7, s19
	v_writelane_b32 v255, s21, 6
	s_add_u32 s20, s18, 0x80000
	v_writelane_b32 v255, s18, 7
	s_addc_u32 s21, s19, 0
	s_nop 0
	v_writelane_b32 v255, s19, 8
	v_writelane_b32 v255, s20, 9
	s_add_u32 s18, s14, 0x80080
	s_nop 0
	v_writelane_b32 v255, s21, 10
	v_writelane_b32 v255, s14, 11
	s_addc_u32 s19, s15, 0
	s_nop 0
	v_writelane_b32 v255, s15, 12
	v_writelane_b32 v255, s18, 13
	s_lshl_b64 s[14:15], s[40:41], 20
	s_nop 0
	v_writelane_b32 v255, s19, 14
	s_mov_b32 s18, s46
	v_writelane_b32 v255, s18, 15
	s_nop 1
	v_writelane_b32 v255, s19, 16
	s_lshl_b64 s[18:19], s[46:47], 20
	s_add_u32 s20, s34, s14
	v_writelane_b32 v255, s34, 17
	s_addc_u32 s21, s35, s15
	s_add_u32 s14, s20, 0x80000
	v_writelane_b32 v255, s35, 18
	s_addc_u32 s15, s21, 0
	v_writelane_b32 v255, s14, 19
	s_add_u32 s18, s6, s18
	s_addc_u32 s19, s7, s19
	v_writelane_b32 v255, s15, 20
	s_movk_i32 s14, 0x3ff
	v_and_or_b32 v0, v0, s14, v202
	s_add_u32 s14, s18, 0x80000
	v_writelane_b32 v255, s18, 21
	s_addc_u32 s15, s19, 0
	s_mov_b64 s[34:35], 0x2000
	v_writelane_b32 v255, s19, 22
	v_writelane_b32 v255, s14, 23
	s_nop 1
	v_writelane_b32 v255, s15, 24
	s_add_u32 s14, s20, 0x80080
	v_writelane_b32 v255, s20, 25
	s_addc_u32 s15, s21, 0
	s_nop 0
	v_writelane_b32 v255, s21, 26
	v_writelane_b32 v255, s14, 27
	s_nop 1
	v_writelane_b32 v255, s15, 28
	s_abs_i32 s14, s70
	s_sub_i32 s15, 1, s14
	s_cmp_lt_u32 s14, 2
	s_cselect_b32 s15, s15, 1
	s_sub_i32 s16, s15, s14
	s_cmp_ge_u32 s15, s14
	s_cselect_b32 s14, s16, s15
	s_cmp_eq_u32 s2, s14
	s_cselect_b64 s[14:15], -1, 0
	v_writelane_b32 v255, s14, 29
	s_lshl_b32 s22, s70, 10
	s_add_i32 s38, 0, 0x20808
	v_writelane_b32 v255, s15, 30
	s_lshl_b32 s14, s2, 8
	s_lshl_b32 s15, s97, 5
	s_add_i32 s14, s14, s15
	v_writelane_b32 v255, s14, 31
	s_lshl_b32 s14, s2, 10
	v_writelane_b32 v255, s14, 32
	s_lshl_b32 s14, s70, 8
	v_writelane_b32 v255, s14, 33
	s_add_i32 s14, s24, 0xa800
	v_writelane_b32 v255, s14, 34
	s_add_i32 s14, s24, 0xc800
	v_writelane_b32 v255, s14, 35
	s_add_i32 s14, s24, 0xd000
	v_writelane_b32 v255, s14, 36
	s_add_i32 s14, s24, 0xd400
	v_writelane_b32 v255, s14, 37
	s_mov_b32 s14, s24
	v_writelane_b32 v255, s14, 38
	s_nop 1
	v_writelane_b32 v255, s15, 39
	s_add_i32 s14, s24, 0xd800
	v_writelane_b32 v255, s14, 40
	s_add_i32 s14, 0, 0x20840
	v_writelane_b32 v255, s14, 41
	s_add_i32 s14, 0, 0x20844
	v_writelane_b32 v255, s14, 42
	s_add_i32 s14, 0, 0x20800
	v_writelane_b32 v255, s14, 43
	s_add_i32 s14, 0, 0x2080c
	v_writelane_b32 v255, s14, 44
	s_add_i32 s14, 0, 0x20804
	v_writelane_b32 v255, s14, 45
	v_cmp_eq_u32_e64 s[14:15], 0, v0
	s_nop 1
	v_writelane_b32 v255, s14, 46
	s_nop 1
	v_writelane_b32 v255, s15, 47
	v_writelane_b32 v255, s56, 48
	s_mov_b64 s[14:15], -1
	s_nop 0
	v_writelane_b32 v255, s57, 49
	v_writelane_b32 v255, s97, 50
	v_writelane_b32 v255, s36, 51
	s_nop 1
	v_writelane_b32 v255, s37, 52
	v_writelane_b32 v255, s22, 53
	s_branch .LBB0_8

;     __host__ __device__ bool next(int i, Unit& u) const {
;         const long L = (long)i * G + c; if (L >= nwg) return false;
;         int wgid = (int)L; { const int q = nwg / NXCD, r = nwg % NXCD, xcd = wgid % NXCD, off = wgid / NXCD; wgid = (xcd < r ? xcd * (q + 1) : r * (q + 1) + (xcd - r) * q) + off; }
;         const int nig = WGM * nN, gid = wgid / nig, fm = gid * WGM, gsz = (nM - fm) < WGM ? (nM - fm) : WGM;
;         u.pm = fm + ((wgid % nig) % gsz); u.pn = (wgid % nig) / gsz; return true;
.LBB0_153:
	s_add_i32 s97, s97, 1
	s_mul_i32 s15, s97, s33
	s_mul_hi_u32 s24, s97, s70
	s_add_i32 s24, s24, s15
	s_mul_i32 s15, s97, s70
	s_add_u32 s54, s15, s2
	s_addc_u32 s55, s24, s3
	v_mov_b64_e32 v[0:1], 0xa00
	v_cmp_lt_i64_e64 s[42:43], s[54:55], v[0:1]
	v_mov_b64_e32 v[0:1], 0x9ff
	v_cmp_gt_i64_e32 vcc, s[54:55], v[0:1]
	s_cbranch_vccnz .LBB0_155
	s_ashr_i32 s14, s54, 31
	s_lshr_b32 s14, s14, 29
	s_add_i32 s14, s54, s14
	s_ashr_i32 s15, s14, 3
	s_and_b32 s14, s14, -8
	s_sub_i32 s14, s54, s14
	s_cmp_lt_i32 s14, 0
	s_movk_i32 s24, 0x141
	s_cselect_b32 s24, s24, 0x140
	s_mul_i32 s14, s14, s24
	s_add_i32 s14, s14, s15
	s_mul_hi_i32 s15, s14, 0x66666667
	s_lshr_b32 s24, s15, 31
	s_ashr_i32 s15, s15, 6
	s_add_i32 s15, s15, s24
	s_lshl_b32 s24, s15, 2
	s_sub_i32 s25, 64, s24
	s_min_i32 s25, s25, 4
	s_abs_i32 s26, s25
	v_cvt_f32_u32_e32 v0, s26
	s_sub_i32 s28, 0, s26
	s_mulk_i32 s15, 0xa0
	s_sub_i32 s14, s14, s15
	v_rcp_iflag_f32_e32 v0, v0
	s_abs_i32 s15, s14
	s_xor_b32 s27, s14, s25
	s_ashr_i32 s27, s27, 31
	v_mul_f32_e32 v0, 0x4f7ffffe, v0
	v_cvt_u32_f32_e32 v0, v0
	s_nop 0
	v_readfirstlane_b32 s29, v0
	s_mul_i32 s28, s28, s29
	s_mul_hi_u32 s28, s29, s28
	s_add_i32 s29, s29, s28
	s_mul_hi_u32 s28, s15, s29
	s_mul_i32 s29, s28, s26
	s_sub_i32 s15, s15, s29
	s_add_i32 s30, s28, 1
	s_sub_i32 s29, s15, s26
	s_cmp_ge_u32 s15, s26
	s_cselect_b32 s28, s30, s28
	s_cselect_b32 s15, s29, s15
	s_add_i32 s29, s28, 1
	s_cmp_ge_u32 s15, s26
	s_cselect_b32 s15, s29, s28
	s_xor_b32 s15, s15, s27
	s_sub_i32 s62, s15, s27
	s_mul_i32 s15, s62, s25
	s_sub_i32 s14, s14, s15
	s_add_i32 s14, s24, s14

;     __host__ __device__ bool next(int i, Unit& u) const {
;     ...
;         const int nig = WGM * nN, gid = wgid / nig, fm = gid * WGM, gsz = (nM - fm) < WGM ? (nM - fm) : WGM;
;         u.pm = fm + ((wgid % nig) % gsz); u.pn = (wgid % nig) / gsz; return true;
.LBB0_770:
	s_ashr_i32 s24, s24, 3
	s_add_i32 s24, s46, s24
	s_ashr_i32 s25, s24, 31
	s_lshr_b32 s25, s25, 25
	s_add_i32 s25, s24, s25
	s_ashr_i32 s26, s25, 7
	s_lshl_b32 s26, s26, 2
	s_sub_i32 s27, 64, s26
	s_min_i32 s27, s27, 4
	s_abs_i32 s28, s27
	v_cvt_f32_u32_e32 v0, s28
	s_sub_i32 s30, 0, s28
	s_andn2_b32 s25, s25, 127
	s_sub_i32 s24, s24, s25
	v_rcp_iflag_f32_e32 v0, v0
	s_abs_i32 s25, s24
	s_xor_b32 s29, s24, s27
	s_ashr_i32 s29, s29, 31
	v_mul_f32_e32 v0, 0x4f7ffffe, v0
	v_cvt_u32_f32_e32 v0, v0
	s_nop 0
	v_readfirstlane_b32 s31, v0
	s_mul_i32 s30, s30, s31
	s_mul_hi_u32 s30, s31, s30
	s_add_i32 s31, s31, s30
	s_mul_hi_u32 s30, s25, s31
	s_mul_i32 s31, s30, s28
	s_sub_i32 s25, s25, s31
	s_add_i32 s44, s30, 1
	s_sub_i32 s31, s25, s28
	s_cmp_ge_u32 s25, s28
	s_cselect_b32 s30, s44, s30
	s_cselect_b32 s25, s31, s25
	s_add_i32 s31, s30, 1
	s_cmp_ge_u32 s25, s28
	s_cselect_b32 s25, s31, s30
	s_xor_b32 s25, s25, s29
	s_sub_i32 s44, s25, s29
	s_mul_i32 s25, s44, s27
	s_sub_i32 s24, s24, s25
	s_add_i32 s46, s26, s24
